# adds: LDS-DMA issue of tile t+1 moved from the step top into the QK block behind its up-front K-fragment reads (first LDS round-trip shadow)
# speedup vs baseline: 1.0033x; 1.0033x over previous
.LBB0_148:
	s_add_i32 s36, s57, -2
	s_and_b32 s74, s36, 1
	s_lshl_b32 s36, s74, 14
	s_lshl_b32 s42, s74, 13
	s_add_i32 s42, s42, 0x14000
	v_add3_u32 v210, s36, v222, v221
	v_add3_u32 v211, s36, v223, v221
	v_add3_u32 v212, s36, v224, v221
	v_add3_u32 v213, s36, v225, v221
	ds_read_b128 v[240:243], v210 offset:49152
	ds_read_b128 v[244:247], v211 offset:49152
	ds_read_b128 v[248:251], v212 offset:49152
	ds_read_b128 v[236:239], v213 offset:49152
	ds_read_b128 v[64:67], v210 offset:49280
	ds_read_b128 v[68:71], v211 offset:49280
	ds_read_b128 v[72:75], v212 offset:49280
	ds_read_b128 v[76:79], v213 offset:49280
	s_add_i32 s37, s57, -1
	s_cmp_ge_u32 s37, s33
	s_cbranch_scc1 .Lkvdma_skip
	s_and_b32 s37, s37, 1
	s_add_i32 s43, s70, 1
	s_cmp_lg_u32 s70, 2
	s_cselect_b32 s43, s43, 0
	v_readlane_b32 s74, v254, 50
	s_lshl_b32 s75, s43, 14
	s_lshl_b32 s74, s74, 11
	s_add_i32 s75, s75, s74
	s_mov_b32 m0, s75
	s_nop 0
	global_load_lds_dwordx4 v[146:147], off
	s_add_i32 m0, s75, 0x380
	s_nop 0
	global_load_lds_dwordx4 v[146:147], off offset:128
	s_lshl_b32 s75, s37, 14
	s_add_i32 s75, s75, s74
	s_add_i32 m0, s75, 0xc000
	s_nop 0
	global_load_lds_dwordx4 v[148:149], off
	s_add_i32 m0, s75, 0xc400
	s_nop 0
	global_load_lds_dwordx4 v[150:151], off
	s_lshl_b32 s75, s37, 13
	s_lshr_b32 s74, s74, 1
	s_add_i32 s75, s75, s74
	s_add_i32 m0, s75, 0x14000
	s_nop 0
	global_load_lds_dwordx4 v[152:153], off
	s_mul_i32 s74, s100, 24
	s_mov_b32 s75, s101
	v_lshl_add_u64 v[146:147], v[146:147], 0, s[74:75]
	v_lshl_add_u64 v[148:149], v[148:149], 0, s[74:75]
	v_lshl_add_u64 v[150:151], v[150:151], 0, s[74:75]
	v_lshl_add_u64 v[152:153], v[152:153], 0, s[100:101]
.Lkvdma_skip:
	v_add3_u32 v234, s42, v227, v226
	v_add3_u32 v235, s42, v228, v226
	s_waitcnt lgkmcnt(7)
	v_mfma_f32_32x32x16_bf16 v[80:95], v[240:243], v[98:101], 0
	ds_read_b128 v[240:243], v234
	s_waitcnt lgkmcnt(7)
	v_mfma_f32_32x32x16_bf16 v[80:95], v[244:247], v[102:105], v[80:95]
	ds_read_b128 v[244:247], v235
	v_add3_u32 v234, s42, v229, v226
	v_add3_u32 v235, s42, v230, v226
	s_waitcnt lgkmcnt(7)
	v_mfma_f32_32x32x16_bf16 v[80:95], v[248:251], v[106:109], v[80:95]
	ds_read_b128 v[248:251], v234
	s_waitcnt lgkmcnt(7)
	v_mfma_f32_32x32x16_bf16 v[80:95], v[236:239], v[110:113], v[80:95]
	ds_read_b128 v[236:239], v235
	s_waitcnt lgkmcnt(7)
	v_mfma_f32_32x32x16_bf16 v[80:95], v[64:67], v[114:117], v[80:95]
	ds_read_b128 v[64:67], v210 offset:57344
	s_waitcnt lgkmcnt(7)
	v_mfma_f32_32x32x16_bf16 v[80:95], v[68:71], v[118:121], v[80:95]
	s_waitcnt lgkmcnt(6)
	v_mfma_f32_32x32x16_bf16 v[80:95], v[72:75], v[122:125], v[80:95]
	s_waitcnt lgkmcnt(5)
	v_mfma_f32_32x32x16_bf16 v[80:95], v[76:79], v[126:129], v[80:95]
	s_waitcnt lgkmcnt(4)
	v_mfma_f32_32x32x16_bf16 v[80:95], v[240:243], v[130:133], v[80:95]
	ds_read_b128 v[240:243], v211 offset:57344
	s_waitcnt lgkmcnt(4)
	v_mfma_f32_32x32x16_bf16 v[80:95], v[244:247], v[138:141], v[80:95]
	ds_read_b128 v[244:247], v212 offset:57344
	s_waitcnt lgkmcnt(4)
	v_mfma_f32_32x32x16_bf16 v[80:95], v[248:251], v[134:137], v[80:95]
	ds_read_b128 v[248:251], v213 offset:57344
	s_waitcnt lgkmcnt(4)
	v_mfma_f32_32x32x16_bf16 v[80:95], v[236:239], v[142:145], v[80:95]
	ds_read_b128 v[236:239], v210 offset:57472
	s_waitcnt lgkmcnt(4)
	v_mfma_f32_32x32x16_bf16 v[64:79], v[64:67], v[98:101], 0
	s_waitcnt lgkmcnt(3)
	v_mfma_f32_32x32x16_bf16 v[64:79], v[240:243], v[102:105], v[64:79]
	ds_read_b128 v[240:243], v211 offset:57472
	s_waitcnt lgkmcnt(3)
	v_mfma_f32_32x32x16_bf16 v[64:79], v[244:247], v[106:109], v[64:79]
	ds_read_b128 v[244:247], v212 offset:57472
	v_add3_u32 v210, s42, v227, v226
	s_waitcnt lgkmcnt(3)
	v_mfma_f32_32x32x16_bf16 v[64:79], v[248:251], v[110:113], v[64:79]
	ds_read_b128 v[248:251], v213 offset:57472
	v_add3_u32 v211, s42, v228, v226
	s_waitcnt lgkmcnt(3)
	v_mfma_f32_32x32x16_bf16 v[64:79], v[236:239], v[114:117], v[64:79]
	ds_read_b128 v[236:239], v210 offset:4096
	v_add3_u32 v212, s42, v229, v226
	s_waitcnt lgkmcnt(3)
	v_mfma_f32_32x32x16_bf16 v[64:79], v[240:243], v[118:121], v[64:79]
	ds_read_b128 v[240:243], v211 offset:4096
	v_add3_u32 v213, s42, v230, v226
	s_waitcnt lgkmcnt(3)
	v_mfma_f32_32x32x16_bf16 v[64:79], v[244:247], v[122:125], v[64:79]
	ds_read_b128 v[244:247], v212 offset:4096
	s_waitcnt lgkmcnt(3)
	v_mfma_f32_32x32x16_bf16 v[64:79], v[248:251], v[126:129], v[64:79]
	ds_read_b128 v[248:251], v213 offset:4096
	s_waitcnt lgkmcnt(3)
	v_mfma_f32_32x32x16_bf16 v[64:79], v[236:239], v[130:133], v[64:79]
	s_waitcnt lgkmcnt(2)
	v_mfma_f32_32x32x16_bf16 v[64:79], v[240:243], v[138:141], v[64:79]
	s_waitcnt lgkmcnt(1)
	v_mfma_f32_32x32x16_bf16 v[64:79], v[244:247], v[134:137], v[64:79]
	s_waitcnt lgkmcnt(0)
	v_mfma_f32_32x32x16_bf16 v[64:79], v[248:251], v[142:145], v[64:79]
	s_add_i32 s36, s8, 63
	s_cmp_le_i32 s36, s2
	s_cselect_b64 s[36:37], -1, 0
	s_cmp_gt_i32 s8, s55
	s_cselect_b64 s[42:43], -1, 0
	s_and_b64 s[36:37], s[36:37], s[42:43]
	s_and_b64 vcc, exec, s[36:37]
	s_cbranch_vccnz .LBB0_150
	v_add_u32_e32 v210, s69, v231
	v_cmp_gt_u32_e32 vcc, s66, v210
	v_add_u32_e32 v211, 0xffefffe0, v210
	s_nop 0
	v_cndmask_b32_e32 v80, v214, v80, vcc
	v_cmp_lt_u32_e32 vcc, s67, v211
	v_add_u32_e32 v211, 0xffefffff, v210
	s_nop 0
	v_cndmask_b32_e32 v64, v214, v64, vcc
	v_cmp_lt_u32_e32 vcc, s67, v211
	v_add_u32_e32 v211, 0xffefffdf, v210
	s_nop 0
	v_cndmask_b32_e32 v81, v214, v81, vcc
	v_cmp_lt_u32_e32 vcc, s67, v211
	v_add_u32_e32 v211, 0xffeffffe, v210
	s_nop 0
	v_cndmask_b32_e32 v65, v214, v65, vcc
	v_cmp_lt_u32_e32 vcc, s67, v211
	v_add_u32_e32 v211, 0xffefffde, v210
	s_nop 0
	v_cndmask_b32_e32 v82, v214, v82, vcc
	v_cmp_lt_u32_e32 vcc, s67, v211
	v_add_u32_e32 v211, 0xffeffffd, v210
	s_nop 0
	v_cndmask_b32_e32 v66, v214, v66, vcc
	v_cmp_lt_u32_e32 vcc, s67, v211
	v_add_u32_e32 v211, 0xffefffdd, v210
	s_nop 0
	v_cndmask_b32_e32 v83, v214, v83, vcc
	v_cmp_lt_u32_e32 vcc, s67, v211
	v_add_u32_e32 v211, 0xffeffff8, v210
	s_nop 0
	v_cndmask_b32_e32 v67, v214, v67, vcc
	v_cmp_lt_u32_e32 vcc, s67, v211
	v_add_u32_e32 v211, 0xffefffd8, v210
	s_nop 0
	v_cndmask_b32_e32 v84, v214, v84, vcc
	v_cmp_lt_u32_e32 vcc, s67, v211
	v_add_u32_e32 v211, 0xffeffff7, v210
	s_nop 0
	v_cndmask_b32_e32 v68, v214, v68, vcc
	v_cmp_lt_u32_e32 vcc, s67, v211
	v_add_u32_e32 v211, 0xffefffd7, v210
	s_nop 0
	v_cndmask_b32_e32 v85, v214, v85, vcc
	v_cmp_lt_u32_e32 vcc, s67, v211
	v_add_u32_e32 v211, 0xffeffff6, v210
	s_nop 0
	v_cndmask_b32_e32 v69, v214, v69, vcc
	v_cmp_lt_u32_e32 vcc, s67, v211
	v_add_u32_e32 v211, 0xffefffd6, v210
	s_nop 0
	v_cndmask_b32_e32 v86, v214, v86, vcc
	v_cmp_lt_u32_e32 vcc, s67, v211
	v_add_u32_e32 v211, 0xffeffff5, v210
	s_nop 0
	v_cndmask_b32_e32 v70, v214, v70, vcc
	v_cmp_lt_u32_e32 vcc, s67, v211
	v_add_u32_e32 v211, 0xffefffd5, v210
	s_nop 0
	v_cndmask_b32_e32 v87, v214, v87, vcc
	v_cmp_lt_u32_e32 vcc, s67, v211
	v_add_u32_e32 v211, 0xffeffff0, v210
	s_nop 0
	v_cndmask_b32_e32 v71, v214, v71, vcc
	v_cmp_lt_u32_e32 vcc, s67, v211
	v_add_u32_e32 v211, 0xffefffd0, v210
	s_nop 0
	v_cndmask_b32_e32 v88, v214, v88, vcc
	v_cmp_lt_u32_e32 vcc, s67, v211
	v_add_u32_e32 v211, 0xffefffef, v210
	s_nop 0
	v_cndmask_b32_e32 v72, v214, v72, vcc
	v_cmp_lt_u32_e32 vcc, s67, v211
	v_add_u32_e32 v211, 0xffefffcf, v210
	s_nop 0
	v_cndmask_b32_e32 v89, v214, v89, vcc
	v_cmp_lt_u32_e32 vcc, s67, v211
	v_add_u32_e32 v211, 0xffefffee, v210
	s_nop 0
	v_cndmask_b32_e32 v73, v214, v73, vcc
	v_cmp_lt_u32_e32 vcc, s67, v211
	v_add_u32_e32 v211, 0xffefffce, v210
	s_nop 0
	v_cndmask_b32_e32 v90, v214, v90, vcc
	v_cmp_lt_u32_e32 vcc, s67, v211
	v_add_u32_e32 v211, 0xffefffed, v210
	s_nop 0
	v_cndmask_b32_e32 v74, v214, v74, vcc
	v_cmp_lt_u32_e32 vcc, s67, v211
	v_add_u32_e32 v211, 0xffefffcd, v210
	s_nop 0
	v_cndmask_b32_e32 v91, v214, v91, vcc
	v_cmp_lt_u32_e32 vcc, s67, v211
	v_add_u32_e32 v211, 0xffefffe8, v210
	s_nop 0
	v_cndmask_b32_e32 v75, v214, v75, vcc
	v_cmp_lt_u32_e32 vcc, s67, v211
	v_add_u32_e32 v211, 0xffefffc8, v210
	s_nop 0
	v_cndmask_b32_e32 v92, v214, v92, vcc
	v_cmp_lt_u32_e32 vcc, s67, v211
	v_add_u32_e32 v211, 0xffefffe7, v210
	s_nop 0
	v_cndmask_b32_e32 v76, v214, v76, vcc
	v_cmp_lt_u32_e32 vcc, s67, v211
	v_add_u32_e32 v211, 0xffefffc7, v210
	s_nop 0
	v_cndmask_b32_e32 v93, v214, v93, vcc
	v_cmp_lt_u32_e32 vcc, s67, v211
	v_add_u32_e32 v211, 0xffefffe6, v210
	s_nop 0
	v_cndmask_b32_e32 v77, v214, v77, vcc
	v_cmp_lt_u32_e32 vcc, s67, v211
	v_add_u32_e32 v211, 0xffefffc6, v210
	s_nop 0
	v_cndmask_b32_e32 v94, v214, v94, vcc
	v_cmp_lt_u32_e32 vcc, s67, v211
	v_add_u32_e32 v211, 0xffefffe5, v210
	v_add_u32_e32 v210, 0xffefffc5, v210
	v_cndmask_b32_e32 v78, v214, v78, vcc
	v_cmp_lt_u32_e32 vcc, s67, v211
	s_nop 1
	v_cndmask_b32_e32 v95, v214, v95, vcc
	v_cmp_lt_u32_e32 vcc, s67, v210
	s_nop 1
	v_cndmask_b32_e32 v79, v214, v79, vcc
